# FF-IN GEMM K-loop: LDS-DMA staging rebalanced 4/4 between SP1 and SP2 segments (was 2/6)
# baseline (speedup 1.0000x reference)
; #define PG8_STAGE(bufoff, gbase, voff) do { _Pragma("unroll") for (int _i = 0; _i < 2; ++_i) \
;         __builtin_amdgcn_global_load_lds((const unsigned*)((const char*)(gbase) + (voff)[_i]), (PG8_LAS unsigned*)(lds + (bufoff) + ldsw + _i * 8192), 16, 0, 0); } while (0)
; #define PG8_WAIT_V(n) asm volatile("s_waitcnt vmcnt(" #n ")" ::: "memory")
; #define PG8_BAR __builtin_amdgcn_s_barrier()
; template <class Epi, class Sched, bool ALIGN_EPI = false, bool SP2 = false>
; __device__ __forceinline__ void gemm_phase(PG8_LAS unsigned char* lds, const Gemm g, const Sched& S, const Epi& E) {
;     ...
;     for (int i = 0; i < 2; ++i) { int R, C; stage_rc(tid * 16 + i * 8192, R, C); const int Rb = Epi::PERM ? ((R & ~31) + perm32(R & 31)) : R;
;         voffA[i] = (unsigned)(R * K + C) * 2u; voffB[i] = (unsigned)(Rb * K + C) * 2u; }
;     const size_t kstep = (size_t)(BK * 2);
;     const size_t hstep = (size_t)HALF * K * 2;
;     const size_t tstep = 2 * hstep;
;     const unsigned ldsw = (unsigned)wid * 1024u;
;     const int aoff = lds_byte(wr * 64 + fr, fq * 8), boff = lds_byte(wc * 32 + fr, fq * 8);
;     ...
;     const char* cA = (const char*)g.A + (size_t)cur.pm * tstep; const char* cB = (const char*)g.Bt + (size_t)cur.pn * tstep;
;     S.a_ready(cur);
;     if constexpr (SP2) {
;         PG8_STAGE(PG8_SB(0, 0), cB, voffB); PG8_STAGE(PG8_SB(0, 1), cB + hstep, voffB); PG8_STAGE(PG8_SA(0, 0), cA, voffA); PG8_STAGE(PG8_SA(0, 1), cA + hstep, voffA);
;         if (wr == 1) PG8_BAR;
;         PG8_WAIT_V(2); PG8_BAR;
;         PG8_STAGE(PG8_SB(1, 0), cB + kstep, voffB); PG8_STAGE(PG8_SA(1, 0), cA + kstep, voffA); PG8_STAGE(PG8_SB(1, 1), cB + hstep + kstep, voffB);
;         PG8_WAIT_V(6); PG8_BAR;
.LBB0_1241:
	s_add_u32 s12, s0, 0x6000000
	s_addc_u32 s13, s1, 0
	s_add_u32 s14, s0, 0xfd00000
	s_addc_u32 s15, s1, 0
	s_add_u32 s16, s0, 0xa500000
	s_addc_u32 s17, s1, 0
	s_mul_i32 s18, s63, 0x8400
	s_mul_hi_u32 s19, s63, 0x8400
	s_waitcnt lgkmcnt(0)
	s_add_u32 s18, s8, s18
	s_addc_u32 s19, s9, s19
	s_mul_i32 s9, s63, 0x2c00
	s_mul_hi_u32 s8, s63, 0x2c00
	s_add_u32 s10, s10, s9
	s_addc_u32 s11, s11, s8
	s_add_u32 s20, s0, 0xa7c0000
	s_addc_u32 s21, s1, 0
	v_bfe_u32 v228, v16, 4, 2
	s_add_u32 s22, s0, 0xaa80000
	v_and_b32_e32 v1, 15, v16
	v_lshlrev_b32_e32 v17, 4, v228
	v_lshlrev_b32_e32 v16, 2, v16
	s_addc_u32 s23, s1, 0
	s_and_b32 s26, s24, 3
	v_lshl_or_b32 v17, v1, 6, v17
	s_lshl_b32 s8, s7, 13
	v_and_b32_e32 v16, 32, v16
	s_add_i32 m0, s53, 0x18000
	v_lshl_add_u64 v[8:9], v[8:9], 0, s[96:97]
	s_lshl_b32 s58, s7, 6
	v_bitop3_b32 v18, v17, s8, v16 bitop3:0xde
	s_lshl_b32 s59, s26, 5
	s_lshl_b32 s8, s26, 12
	s_waitcnt vmcnt(2)
	s_barrier
	global_load_lds_dwordx4 v[8:9], off
	v_lshl_add_u64 v[6:7], v[6:7], 0, s[96:97]
	s_add_i32 m0, s53, 0x1a000
	s_add_i32 s60, s53, 0x8000
	s_add_i32 s61, s53, 0xa000
	v_bitop3_b32 v229, v17, s8, v16 bitop3:0xde
	global_load_lds_dwordx4 v[6:7], off
	v_lshl_add_u64 v[4:5], v[4:5], 0, s[96:97]
	s_mov_b32 m0, s60
	s_add_u32 s8, s44, 0x40080
	global_load_lds_dwordx4 v[4:5], off
	v_lshl_add_u64 v[2:3], v[2:3], 0, s[96:97]
	s_mov_b32 m0, s61
	s_addc_u32 s9, s45, 0
	global_load_lds_dwordx4 v[2:3], off
	s_lshl_b32 s27, s26, 9
	s_lshl_b32 s28, s7, 11
	s_cmpk_gt_u32 s6, 0xff
	s_cselect_b64 s[8:9], -1, 0
	s_cmpk_lt_u32 s6, 0x100
	s_cselect_b64 s[24:25], -1, 0
	s_and_b64 s[6:7], s[24:25], exec
	v_lshlrev_b32_e32 v2, 14, v14
	s_cselect_b32 s6, 4, 0
	s_add_i32 s7, 0, 0x20000
	v_and_b32_e32 v2, 0xffff8000, v2
	s_or_b32 s6, s6, s26
	s_add_i32 s62, s7, s27
	v_lshl_add_u32 v2, v13, 11, v2
	v_and_b32_e32 v3, 1, v14
	s_lshl_b32 s6, s6, 9
	s_add_i32 s63, s62, s28
	v_lshl_or_b32 v2, v3, 6, v2
	s_add_u32 s26, s18, 0x2c00
	v_lshl_add_u32 v188, v15, 1, v2
	v_lshlrev_b32_e32 v2, 14, v10
	s_addc_u32 s27, s19, 0
	v_and_b32_e32 v2, 0xffff8000, v2
	s_waitcnt vmcnt(4)
	s_add_u32 s28, s18, 0x5800
	v_lshl_add_u32 v2, v11, 11, v2
	v_and_b32_e32 v3, 1, v10
	s_addc_u32 s29, s19, 0
	s_add_i32 s64, s7, s6
	s_lshl_b32 s6, s30, 2
	v_lshl_or_b32 v2, v3, 6, v2
	s_add_i32 s64, s64, s6
	v_mov_b32_e32 v189, v0
	v_lshl_add_u32 v190, v12, 1, v2
	v_mov_b32_e32 v191, v0
	v_add_u32_e32 v230, 0, v18
	s_xor_b64 s[30:31], s[8:9], -1
	v_readlane_b32 s33, v254, 36
	v_readlane_b32 s42, v254, 61
	s_barrier
	v_readlane_b32 s43, v254, 62
	s_branch .LBB0_1244

; #define PG8_STAGE(bufoff, gbase, voff) do { _Pragma("unroll") for (int _i = 0; _i < 2; ++_i) \
;         __builtin_amdgcn_global_load_lds((const unsigned*)((const char*)(gbase) + (voff)[_i]), (PG8_LAS unsigned*)(lds + (bufoff) + ldsw + _i * 8192), 16, 0, 0); } while (0)
; #define PG8_LDA(dst, b, h) do { _Pragma("unroll") for (int m = 0; m < 4; ++m) _Pragma("unroll") for (int k = 0; k < 2; ++k) dst[m][k] = *(const PG8_LAS bf16x8*)(lds + PG8_SA(b, h) + aoff + m * 2048 + k * 1024); } while (0)
; #define PG8_LDB(dst, b, h) do { _Pragma("unroll") for (int n = 0; n < 2; ++n) _Pragma("unroll") for (int k = 0; k < 2; ++k) dst[n][k] = *(const PG8_LAS bf16x8*)(lds + PG8_SB(b, h) + boff + n * 2048 + k * 1024); } while (0)
; #define PG8_MMA(ai, bj, At, Bt) do { __builtin_amdgcn_s_setprio(1); _Pragma("unroll") for (int m = 0; m < 4; ++m) _Pragma("unroll") for (int n = 0; n < 2; ++n) _Pragma("unroll") for (int k = 0; k < 2; ++k) \
;         acc[ai][bj][m][n] = __builtin_amdgcn_mfma_f32_16x16x32_bf16(Bt[n][k], At[m][k], acc[ai][bj][m][n], 0, 0, 0); __builtin_amdgcn_s_setprio(0); } while (0)
; #define PG8_WAIT_V(n) asm volatile("s_waitcnt vmcnt(" #n ")" ::: "memory")
; #define PG8_WAIT_L(n) asm volatile("s_waitcnt lgkmcnt(" #n ")" ::: "memory")
; template <class Epi, class Sched, bool ALIGN_EPI = false, bool SP2 = false>
; __device__ __forceinline__ void gemm_phase(PG8_LAS unsigned char* lds, const Gemm g, const Sched& S, const Epi& E) {
;     ...
;             const bool last = (t == nt - 2);
;             const char* a1 = cA + (size_t)(t + 1) * kstep;
;             const char* a2 = last ? nA : cA + (size_t)(t + 2) * kstep; const char* b2 = last ? nB : cB + (size_t)(t + 2) * kstep;
;             const char* a3 = a2 + kstep; const char* b3 = b2 + kstep;
;             if (last && has_next) S.a_ready(nxt);
;             if constexpr (SP2) {
;             PG8_LDB(B0, 0, 0); PG8_LDB(B1, 0, 1); PG8_SCHED; PG8_LDA(At, 0, 0); PG8_STAGE(PG8_SA(1, 1), a1 + hstep, voffA);
;             PG8_WAIT_V(8); PG8_WAIT_L(0); PG8_BAR; PG8_MMA(0, 0, At, B0); PG8_MMA(0, 1, At, B1); PG8_BAR; PG8_SCHED;
;             PG8_LDA(At, 0, 1); PG8_STAGE(PG8_SB(0, 0), b2, voffB); PG8_STAGE(PG8_SB(0, 1), b2 + hstep, voffB); PG8_STAGE(PG8_SA(0, 0), a2, voffA);
;             PG8_WAIT_V(8); PG8_WAIT_L(0); PG8_BAR; PG8_MMA(1, 0, At, B0); PG8_MMA(1, 1, At, B1); PG8_BAR; PG8_SCHED;
.LBB0_1247:
	s_add_u32 s44, s8, 0xfffc0080
	s_addc_u32 s45, s9, -1
	s_add_i32 s69, 0, 0x10000
	s_cmp_eq_u32 s68, 12
	s_cselect_b32 s47, s37, s45
	s_cselect_b32 s46, s43, s44
	s_cselect_b32 s45, s35, s67
	s_cselect_b32 s44, s65, s66
	s_add_i32 s72, 0, 0x14000
	v_add_u32_e32 v118, s69, v229
	v_add_u32_e32 v134, s72, v229
	ds_read_b128 v[106:109], v118
	ds_read_b128 v[110:113], v118 offset:1024
	ds_read_b128 v[114:117], v118 offset:2048
	ds_read_b128 v[118:121], v118 offset:3072
	ds_read_b128 v[122:125], v134
	ds_read_b128 v[126:129], v134 offset:1024
	ds_read_b128 v[130:133], v134 offset:2048
	ds_read_b128 v[134:137], v134 offset:3072
	s_add_u32 s98, s66, 0x3ff80
	s_addc_u32 s99, s67, 0
	v_lshl_add_u64 v[212:213], s[98:99], 0, v[184:185]
	s_add_i32 m0, s53, 0x1c000
	s_nop 0
	global_load_lds_dwordx4 v[212:213], off
	v_lshl_add_u64 v[212:213], s[98:99], 0, v[180:181]
	s_add_i32 m0, s53, 0x1e000
	s_nop 0
	global_load_lds_dwordx4 v[212:213], off
	v_lshl_add_u64 v[212:213], s[8:9], 0, v[188:189]
	s_add_i32 m0, s53, 0xc000
	ds_read_b128 v[162:165], v230
	ds_read_b128 v[166:169], v230 offset:1024
	ds_read_b128 v[170:173], v230 offset:2048
	ds_read_b128 v[192:195], v230 offset:3072
	ds_read_b128 v[196:199], v230 offset:4096
	ds_read_b128 v[200:203], v230 offset:5120
	ds_read_b128 v[204:207], v230 offset:6144
	ds_read_b128 v[208:211], v230 offset:7168
	global_load_lds_dwordx4 v[212:213], off
	v_lshl_add_u64 v[212:213], s[8:9], 0, v[190:191]
	s_add_i32 m0, s53, 0xe000
	s_nop 0
	global_load_lds_dwordx4 v[212:213], off
	s_waitcnt vmcnt(8)
	s_waitcnt lgkmcnt(0)
	s_barrier
	s_setprio 1
	s_waitcnt lgkmcnt(0)
	v_mfma_f32_16x16x32_bf16 v[158:161], v[106:109], v[162:165], v[158:161]
	v_mfma_f32_16x16x32_bf16 v[154:157], v[114:117], v[162:165], v[154:157]
	v_mfma_f32_16x16x32_bf16 v[142:145], v[106:109], v[170:173], v[142:145]
	v_mfma_f32_16x16x32_bf16 v[138:141], v[114:117], v[170:173], v[138:141]
	v_mfma_f32_16x16x32_bf16 v[94:97], v[106:109], v[196:199], v[94:97]
	v_mfma_f32_16x16x32_bf16 v[90:93], v[114:117], v[196:199], v[90:93]
	v_mfma_f32_16x16x32_bf16 v[78:81], v[106:109], v[204:207], v[78:81]
	v_mfma_f32_16x16x32_bf16 v[74:77], v[114:117], v[204:207], v[74:77]
	v_mfma_f32_16x16x32_bf16 v[158:161], v[110:113], v[166:169], v[158:161]
	v_mfma_f32_16x16x32_bf16 v[154:157], v[118:121], v[166:169], v[154:157]
	v_mfma_f32_16x16x32_bf16 v[142:145], v[110:113], v[192:195], v[142:145]
	v_mfma_f32_16x16x32_bf16 v[138:141], v[118:121], v[192:195], v[138:141]
	v_mfma_f32_16x16x32_bf16 v[94:97], v[110:113], v[200:203], v[94:97]
	v_mfma_f32_16x16x32_bf16 v[90:93], v[118:121], v[200:203], v[90:93]
	v_mfma_f32_16x16x32_bf16 v[78:81], v[110:113], v[208:211], v[78:81]
	v_mfma_f32_16x16x32_bf16 v[74:77], v[118:121], v[208:211], v[74:77]
	s_setprio 0
	s_setprio 1
	v_mfma_f32_16x16x32_bf16 v[150:153], v[122:125], v[162:165], v[150:153]
	v_mfma_f32_16x16x32_bf16 v[146:149], v[130:133], v[162:165], v[146:149]
	v_mfma_f32_16x16x32_bf16 v[102:105], v[122:125], v[170:173], v[102:105]
	v_mfma_f32_16x16x32_bf16 v[98:101], v[130:133], v[170:173], v[98:101]
	v_mfma_f32_16x16x32_bf16 v[86:89], v[122:125], v[196:199], v[86:89]
	v_mfma_f32_16x16x32_bf16 v[82:85], v[130:133], v[196:199], v[82:85]
	v_mfma_f32_16x16x32_bf16 v[70:73], v[122:125], v[204:207], v[70:73]
	v_mfma_f32_16x16x32_bf16 v[66:69], v[130:133], v[204:207], v[66:69]
	v_mfma_f32_16x16x32_bf16 v[150:153], v[126:129], v[166:169], v[150:153]
	v_mfma_f32_16x16x32_bf16 v[146:149], v[134:137], v[166:169], v[146:149]
	v_mfma_f32_16x16x32_bf16 v[102:105], v[126:129], v[192:195], v[102:105]
	v_mfma_f32_16x16x32_bf16 v[98:101], v[134:137], v[192:195], v[98:101]
	v_mfma_f32_16x16x32_bf16 v[86:89], v[126:129], v[200:203], v[86:89]
	v_mfma_f32_16x16x32_bf16 v[82:85], v[134:137], v[200:203], v[82:85]
	v_mfma_f32_16x16x32_bf16 v[70:73], v[126:129], v[208:211], v[70:73]
	v_mfma_f32_16x16x32_bf16 v[66:69], v[134:137], v[208:211], v[66:69]
	s_setprio 0
	s_barrier
	s_add_i32 s69, s69, s52
	v_lshl_add_u64 v[212:213], s[44:45], 0, v[184:185]
	s_mov_b32 m0, s69
	ds_read_b128 v[162:165], v230 offset:16384
	ds_read_b128 v[166:169], v230 offset:17408
	ds_read_b128 v[170:173], v230 offset:18432
	ds_read_b128 v[192:195], v230 offset:19456
	ds_read_b128 v[196:199], v230 offset:20480
	ds_read_b128 v[200:203], v230 offset:21504
	ds_read_b128 v[204:207], v230 offset:22528
	ds_read_b128 v[208:211], v230 offset:23552
	global_load_lds_dwordx4 v[212:213], off
	s_add_i32 m0, s69, 0x2000
	v_lshl_add_u64 v[214:215], s[44:45], 0, v[180:181]
	global_load_lds_dwordx4 v[214:215], off
	v_lshl_add_u64 v[218:219], s[46:47], 0, v[182:183]
	v_lshl_add_u64 v[216:217], s[46:47], 0, v[186:187]
	s_mov_b32 m0, s53
	s_nop 0
	global_load_lds_dwordx4 v[216:217], off
	s_mov_b32 m0, s54
	s_nop 0
	global_load_lds_dwordx4 v[218:219], off
	s_waitcnt vmcnt(6)
	s_waitcnt lgkmcnt(0)
	s_barrier
; #define PG8_STAGE(bufoff, gbase, voff) do { _Pragma("unroll") for (int _i = 0; _i < 2; ++_i) \
;         __builtin_amdgcn_global_load_lds((const unsigned*)((const char*)(gbase) + (voff)[_i]), (PG8_LAS unsigned*)(lds + (bufoff) + ldsw + _i * 8192), 16, 0, 0); } while (0)
; #define PG8_LDA(dst, b, h) do { _Pragma("unroll") for (int m = 0; m < 4; ++m) _Pragma("unroll") for (int k = 0; k < 2; ++k) dst[m][k] = *(const PG8_LAS bf16x8*)(lds + PG8_SA(b, h) + aoff + m * 2048 + k * 1024); } while (0)
; #define PG8_LDB(dst, b, h) do { _Pragma("unroll") for (int n = 0; n < 2; ++n) _Pragma("unroll") for (int k = 0; k < 2; ++k) dst[n][k] = *(const PG8_LAS bf16x8*)(lds + PG8_SB(b, h) + boff + n * 2048 + k * 1024); } while (0)
; #define PG8_MMA(ai, bj, At, Bt) do { __builtin_amdgcn_s_setprio(1); _Pragma("unroll") for (int m = 0; m < 4; ++m) _Pragma("unroll") for (int n = 0; n < 2; ++n) _Pragma("unroll") for (int k = 0; k < 2; ++k) \
;         acc[ai][bj][m][n] = __builtin_amdgcn_mfma_f32_16x16x32_bf16(Bt[n][k], At[m][k], acc[ai][bj][m][n], 0, 0, 0); __builtin_amdgcn_s_setprio(0); } while (0)
; #define PG8_WAIT_V(n) asm volatile("s_waitcnt vmcnt(" #n ")" ::: "memory")
; #define PG8_WAIT_L(n) asm volatile("s_waitcnt lgkmcnt(" #n ")" ::: "memory")
; #define PG8_BAR __builtin_amdgcn_s_barrier()
; #define PG8_SCHED __builtin_amdgcn_sched_barrier(0)
; template <class Epi, class Sched, bool ALIGN_EPI = false, bool SP2 = false>
; __device__ __forceinline__ void gemm_phase(PG8_LAS unsigned char* lds, const Gemm g, const Sched& S, const Epi& E) {
;     ...
;             PG8_WAIT_V(8); PG8_WAIT_L(0); PG8_BAR; PG8_MMA(1, 0, At, B0); PG8_MMA(1, 1, At, B1); PG8_BAR; PG8_SCHED;
;             PG8_LDB(B0, 1, 0); PG8_LDB(B1, 1, 1); PG8_SCHED; PG8_LDA(At, 1, 0); PG8_STAGE(PG8_SA(0, 1), a2 + hstep, voffA);
;             PG8_WAIT_V(8); PG8_WAIT_L(0); PG8_BAR; PG8_MMA(0, 0, At, B0); PG8_MMA(0, 1, At, B1); PG8_BAR; PG8_SCHED;
	s_setprio 1
	s_waitcnt lgkmcnt(0)
	v_mfma_f32_16x16x32_bf16 v[62:65], v[106:109], v[162:165], v[62:65]
	v_mfma_f32_16x16x32_bf16 v[58:61], v[114:117], v[162:165], v[58:61]
	v_mfma_f32_16x16x32_bf16 v[46:49], v[106:109], v[170:173], v[46:49]
	v_mfma_f32_16x16x32_bf16 v[42:45], v[114:117], v[170:173], v[42:45]
	v_mfma_f32_16x16x32_bf16 v[30:33], v[106:109], v[196:199], v[30:33]
	v_mfma_f32_16x16x32_bf16 v[26:29], v[114:117], v[196:199], v[26:29]
	v_mfma_f32_16x16x32_bf16 v[14:17], v[106:109], v[204:207], v[14:17]
	v_mfma_f32_16x16x32_bf16 v[10:13], v[114:117], v[204:207], v[10:13]
	v_mfma_f32_16x16x32_bf16 v[62:65], v[110:113], v[166:169], v[62:65]
	v_mfma_f32_16x16x32_bf16 v[58:61], v[118:121], v[166:169], v[58:61]
	v_mfma_f32_16x16x32_bf16 v[46:49], v[110:113], v[192:195], v[46:49]
	v_mfma_f32_16x16x32_bf16 v[42:45], v[118:121], v[192:195], v[42:45]
	v_mfma_f32_16x16x32_bf16 v[30:33], v[110:113], v[200:203], v[30:33]
	v_mfma_f32_16x16x32_bf16 v[26:29], v[118:121], v[200:203], v[26:29]
	v_mfma_f32_16x16x32_bf16 v[14:17], v[110:113], v[208:211], v[14:17]
	v_mfma_f32_16x16x32_bf16 v[10:13], v[118:121], v[208:211], v[10:13]
	s_setprio 0
	s_setprio 1
	v_mfma_f32_16x16x32_bf16 v[54:57], v[122:125], v[162:165], v[54:57]
	v_mfma_f32_16x16x32_bf16 v[50:53], v[130:133], v[162:165], v[50:53]
	v_mfma_f32_16x16x32_bf16 v[38:41], v[122:125], v[170:173], v[38:41]
	v_mfma_f32_16x16x32_bf16 v[34:37], v[130:133], v[170:173], v[34:37]
	v_mfma_f32_16x16x32_bf16 v[22:25], v[122:125], v[196:199], v[22:25]
	v_mfma_f32_16x16x32_bf16 v[18:21], v[130:133], v[196:199], v[18:21]
	v_mfma_f32_16x16x32_bf16 v[6:9], v[122:125], v[204:207], v[6:9]
	v_mfma_f32_16x16x32_bf16 v[2:5], v[130:133], v[204:207], v[2:5]
	v_mfma_f32_16x16x32_bf16 v[54:57], v[126:129], v[166:169], v[54:57]
	v_mfma_f32_16x16x32_bf16 v[50:53], v[134:137], v[166:169], v[50:53]
	v_mfma_f32_16x16x32_bf16 v[38:41], v[126:129], v[192:195], v[38:41]
	v_mfma_f32_16x16x32_bf16 v[34:37], v[134:137], v[192:195], v[34:37]
	v_mfma_f32_16x16x32_bf16 v[22:25], v[126:129], v[200:203], v[22:25]
	v_mfma_f32_16x16x32_bf16 v[18:21], v[134:137], v[200:203], v[18:21]
	v_mfma_f32_16x16x32_bf16 v[6:9], v[126:129], v[208:211], v[6:9]
	v_mfma_f32_16x16x32_bf16 v[2:5], v[134:137], v[208:211], v[2:5]
	s_setprio 0
	s_barrier
	s_add_i32 s69, 0, 0x18000
	s_add_i32 s70, 0, 0x1c000
	v_add_u32_e32 v118, s69, v229
	v_add_u32_e32 v134, s70, v229
	ds_read_b128 v[106:109], v118
	ds_read_b128 v[110:113], v118 offset:1024
	ds_read_b128 v[114:117], v118 offset:2048
	ds_read_b128 v[118:121], v118 offset:3072
	ds_read_b128 v[122:125], v134
	ds_read_b128 v[126:129], v134 offset:1024
	ds_read_b128 v[130:133], v134 offset:2048
	ds_read_b128 v[134:137], v134 offset:3072
	s_add_u32 s98, s44, 0x40000
	s_addc_u32 s99, s45, 0
	v_lshl_add_u64 v[220:221], s[98:99], 0, v[184:185]
	s_add_i32 m0, s53, 0x14000
	s_nop 0
	global_load_lds_dwordx4 v[220:221], off
	v_lshl_add_u64 v[220:221], s[98:99], 0, v[180:181]
	s_add_i32 m0, s53, 0x16000
	s_nop 0
	global_load_lds_dwordx4 v[220:221], off
	s_add_u32 s46, s46, 0x40000
	s_addc_u32 s47, s47, 0
	s_mov_b32 m0, s55
	v_lshl_add_u64 v[220:221], s[46:47], 0, v[186:187]
	ds_read_b128 v[162:165], v230 offset:32768
	ds_read_b128 v[166:169], v230 offset:33792
	ds_read_b128 v[170:173], v230 offset:34816
	ds_read_b128 v[192:195], v230 offset:35840
	ds_read_b128 v[196:199], v230 offset:36864
	ds_read_b128 v[200:203], v230 offset:37888
	ds_read_b128 v[204:207], v230 offset:38912
	ds_read_b128 v[208:211], v230 offset:39936
	global_load_lds_dwordx4 v[220:221], off
	v_lshl_add_u64 v[220:221], s[46:47], 0, v[182:183]
	s_mov_b32 m0, s56
	s_nop 0
	global_load_lds_dwordx4 v[220:221], off
	s_waitcnt vmcnt(8)
	s_waitcnt lgkmcnt(0)
	s_barrier
; #define PG8_STAGE(bufoff, gbase, voff) do { _Pragma("unroll") for (int _i = 0; _i < 2; ++_i) \
;         __builtin_amdgcn_global_load_lds((const unsigned*)((const char*)(gbase) + (voff)[_i]), (PG8_LAS unsigned*)(lds + (bufoff) + ldsw + _i * 8192), 16, 0, 0); } while (0)
; #define PG8_LDA(dst, b, h) do { _Pragma("unroll") for (int m = 0; m < 4; ++m) _Pragma("unroll") for (int k = 0; k < 2; ++k) dst[m][k] = *(const PG8_LAS bf16x8*)(lds + PG8_SA(b, h) + aoff + m * 2048 + k * 1024); } while (0)
; #define PG8_LDB(dst, b, h) do { _Pragma("unroll") for (int n = 0; n < 2; ++n) _Pragma("unroll") for (int k = 0; k < 2; ++k) dst[n][k] = *(const PG8_LAS bf16x8*)(lds + PG8_SB(b, h) + boff + n * 2048 + k * 1024); } while (0)
; template <class Epi, class Sched, bool ALIGN_EPI = false, bool SP2 = false>
; __device__ __forceinline__ void gemm_phase(PG8_LAS unsigned char* lds, const Gemm g, const Sched& S, const Epi& E) {
;     ...
;         for (int t = 0; t < nt; t += 2) {
;             const bool last = (t == nt - 2);
;             const char* a1 = cA + (size_t)(t + 1) * kstep;
;             const char* a2 = last ? nA : cA + (size_t)(t + 2) * kstep; const char* b2 = last ? nB : cB + (size_t)(t + 2) * kstep;
;             const char* a3 = a2 + kstep; const char* b3 = b2 + kstep;
;             if (last && has_next) S.a_ready(nxt);
;             if constexpr (SP2) {
;             PG8_LDB(B0, 0, 0); PG8_LDB(B1, 0, 1); PG8_SCHED; PG8_LDA(At, 0, 0); PG8_STAGE(PG8_SA(1, 1), a1 + hstep, voffA);
;             PG8_WAIT_V(8); PG8_WAIT_L(0); PG8_BAR; PG8_MMA(0, 0, At, B0); PG8_MMA(0, 1, At, B1); PG8_BAR; PG8_SCHED;
;             PG8_LDA(At, 0, 1); PG8_STAGE(PG8_SB(0, 0), b2, voffB); PG8_STAGE(PG8_SB(0, 1), b2 + hstep, voffB); PG8_STAGE(PG8_SA(0, 0), a2, voffA);
;             PG8_WAIT_V(8); PG8_WAIT_L(0); PG8_BAR; PG8_MMA(1, 0, At, B0); PG8_MMA(1, 1, At, B1); PG8_BAR; PG8_SCHED;
;             PG8_LDB(B0, 1, 0); PG8_LDB(B1, 1, 1); PG8_SCHED; PG8_LDA(At, 1, 0); PG8_STAGE(PG8_SA(0, 1), a2 + hstep, voffA);
;             PG8_WAIT_V(8); PG8_WAIT_L(0); PG8_BAR; PG8_MMA(0, 0, At, B0); PG8_MMA(0, 1, At, B1); PG8_BAR; PG8_SCHED;
;             PG8_LDA(At, 1, 1); PG8_STAGE(PG8_SB(1, 0), b3, voffB); PG8_STAGE(PG8_SB(1, 1), b3 + hstep, voffB); PG8_STAGE(PG8_SA(1, 0), a3, voffA);
;             PG8_WAIT_V(8); PG8_WAIT_L(0); PG8_BAR; PG8_MMA(1, 0, At, B0); PG8_MMA(1, 1, At, B1); PG8_BAR; PG8_SCHED;
	s_setprio 1
	s_waitcnt lgkmcnt(0)
	v_mfma_f32_16x16x32_bf16 v[158:161], v[106:109], v[162:165], v[158:161]
	v_mfma_f32_16x16x32_bf16 v[154:157], v[114:117], v[162:165], v[154:157]
	v_mfma_f32_16x16x32_bf16 v[142:145], v[106:109], v[170:173], v[142:145]
	v_mfma_f32_16x16x32_bf16 v[138:141], v[114:117], v[170:173], v[138:141]
	v_mfma_f32_16x16x32_bf16 v[94:97], v[106:109], v[196:199], v[94:97]
	v_mfma_f32_16x16x32_bf16 v[90:93], v[114:117], v[196:199], v[90:93]
	v_mfma_f32_16x16x32_bf16 v[78:81], v[106:109], v[204:207], v[78:81]
	v_mfma_f32_16x16x32_bf16 v[74:77], v[114:117], v[204:207], v[74:77]
	v_mfma_f32_16x16x32_bf16 v[158:161], v[110:113], v[166:169], v[158:161]
	v_mfma_f32_16x16x32_bf16 v[154:157], v[118:121], v[166:169], v[154:157]
	v_mfma_f32_16x16x32_bf16 v[142:145], v[110:113], v[192:195], v[142:145]
	v_mfma_f32_16x16x32_bf16 v[138:141], v[118:121], v[192:195], v[138:141]
	v_mfma_f32_16x16x32_bf16 v[94:97], v[110:113], v[200:203], v[94:97]
	v_mfma_f32_16x16x32_bf16 v[90:93], v[118:121], v[200:203], v[90:93]
	v_mfma_f32_16x16x32_bf16 v[78:81], v[110:113], v[208:211], v[78:81]
	v_mfma_f32_16x16x32_bf16 v[74:77], v[118:121], v[208:211], v[74:77]
	s_setprio 0
	s_setprio 1
	v_mfma_f32_16x16x32_bf16 v[150:153], v[122:125], v[162:165], v[150:153]
	v_mfma_f32_16x16x32_bf16 v[146:149], v[130:133], v[162:165], v[146:149]
	v_mfma_f32_16x16x32_bf16 v[102:105], v[122:125], v[170:173], v[102:105]
	v_mfma_f32_16x16x32_bf16 v[98:101], v[130:133], v[170:173], v[98:101]
	v_mfma_f32_16x16x32_bf16 v[86:89], v[122:125], v[196:199], v[86:89]
	v_mfma_f32_16x16x32_bf16 v[82:85], v[130:133], v[196:199], v[82:85]
	v_mfma_f32_16x16x32_bf16 v[70:73], v[122:125], v[204:207], v[70:73]
	v_mfma_f32_16x16x32_bf16 v[66:69], v[130:133], v[204:207], v[66:69]
	v_mfma_f32_16x16x32_bf16 v[150:153], v[126:129], v[166:169], v[150:153]
	v_mfma_f32_16x16x32_bf16 v[146:149], v[134:137], v[166:169], v[146:149]
	v_mfma_f32_16x16x32_bf16 v[102:105], v[126:129], v[192:195], v[102:105]
	v_mfma_f32_16x16x32_bf16 v[98:101], v[134:137], v[192:195], v[98:101]
	v_mfma_f32_16x16x32_bf16 v[86:89], v[126:129], v[200:203], v[86:89]
	v_mfma_f32_16x16x32_bf16 v[82:85], v[134:137], v[200:203], v[82:85]
	v_mfma_f32_16x16x32_bf16 v[70:73], v[126:129], v[208:211], v[70:73]
	v_mfma_f32_16x16x32_bf16 v[66:69], v[134:137], v[208:211], v[66:69]
	s_setprio 0
	s_barrier
	s_add_i32 s46, s69, s52
	v_lshl_add_u64 v[212:213], v[212:213], 0, s[96:97]
	s_mov_b32 m0, s46
	ds_read_b128 v[162:165], v230 offset:49152
	ds_read_b128 v[166:169], v230 offset:50176
	ds_read_b128 v[170:173], v230 offset:51200
	ds_read_b128 v[192:195], v230 offset:52224
	ds_read_b128 v[196:199], v230 offset:53248
	ds_read_b128 v[200:203], v230 offset:54272
	ds_read_b128 v[204:207], v230 offset:55296
	ds_read_b128 v[208:211], v230 offset:56320
	global_load_lds_dwordx4 v[212:213], off
	s_add_i32 m0, s46, 0x2000
	v_lshl_add_u64 v[212:213], v[214:215], 0, s[96:97]
	global_load_lds_dwordx4 v[212:213], off
	v_lshl_add_u64 v[212:213], v[216:217], 0, s[96:97]
	s_mov_b32 m0, s60
	s_nop 0
	global_load_lds_dwordx4 v[212:213], off
	v_lshl_add_u64 v[212:213], v[218:219], 0, s[96:97]
	s_mov_b32 m0, s61
	s_nop 0
	global_load_lds_dwordx4 v[212:213], off
	s_waitcnt vmcnt(6)
	s_waitcnt lgkmcnt(0)
	s_barrier
	s_setprio 1
	s_waitcnt lgkmcnt(0)
	v_mfma_f32_16x16x32_bf16 v[62:65], v[106:109], v[162:165], v[62:65]
	v_mfma_f32_16x16x32_bf16 v[58:61], v[114:117], v[162:165], v[58:61]
	v_mfma_f32_16x16x32_bf16 v[46:49], v[106:109], v[170:173], v[46:49]
	v_mfma_f32_16x16x32_bf16 v[42:45], v[114:117], v[170:173], v[42:45]
	v_mfma_f32_16x16x32_bf16 v[30:33], v[106:109], v[196:199], v[30:33]
	v_mfma_f32_16x16x32_bf16 v[26:29], v[114:117], v[196:199], v[26:29]
	v_mfma_f32_16x16x32_bf16 v[14:17], v[106:109], v[204:207], v[14:17]
	v_mfma_f32_16x16x32_bf16 v[10:13], v[114:117], v[204:207], v[10:13]
	v_mfma_f32_16x16x32_bf16 v[62:65], v[110:113], v[166:169], v[62:65]
	v_mfma_f32_16x16x32_bf16 v[58:61], v[118:121], v[166:169], v[58:61]
	v_mfma_f32_16x16x32_bf16 v[46:49], v[110:113], v[192:195], v[46:49]
	v_mfma_f32_16x16x32_bf16 v[42:45], v[118:121], v[192:195], v[42:45]
	v_mfma_f32_16x16x32_bf16 v[30:33], v[110:113], v[200:203], v[30:33]
	v_mfma_f32_16x16x32_bf16 v[26:29], v[118:121], v[200:203], v[26:29]
	v_mfma_f32_16x16x32_bf16 v[14:17], v[110:113], v[208:211], v[14:17]
	v_mfma_f32_16x16x32_bf16 v[10:13], v[118:121], v[208:211], v[10:13]
	s_setprio 0
	s_setprio 1
	v_mfma_f32_16x16x32_bf16 v[54:57], v[122:125], v[162:165], v[54:57]
	v_mfma_f32_16x16x32_bf16 v[50:53], v[130:133], v[162:165], v[50:53]
	v_mfma_f32_16x16x32_bf16 v[38:41], v[122:125], v[170:173], v[38:41]
	v_mfma_f32_16x16x32_bf16 v[34:37], v[130:133], v[170:173], v[34:37]
	v_mfma_f32_16x16x32_bf16 v[22:25], v[122:125], v[196:199], v[22:25]
	v_mfma_f32_16x16x32_bf16 v[18:21], v[130:133], v[196:199], v[18:21]
	v_mfma_f32_16x16x32_bf16 v[6:9], v[122:125], v[204:207], v[6:9]
	v_mfma_f32_16x16x32_bf16 v[2:5], v[130:133], v[204:207], v[2:5]
	v_mfma_f32_16x16x32_bf16 v[54:57], v[126:129], v[166:169], v[54:57]
	v_mfma_f32_16x16x32_bf16 v[50:53], v[134:137], v[166:169], v[50:53]
	v_mfma_f32_16x16x32_bf16 v[38:41], v[126:129], v[192:195], v[38:41]
	v_mfma_f32_16x16x32_bf16 v[34:37], v[134:137], v[192:195], v[34:37]
	v_mfma_f32_16x16x32_bf16 v[22:25], v[126:129], v[200:203], v[22:25]
	v_mfma_f32_16x16x32_bf16 v[18:21], v[134:137], v[200:203], v[18:21]
	v_mfma_f32_16x16x32_bf16 v[6:9], v[126:129], v[208:211], v[6:9]
	v_mfma_f32_16x16x32_bf16 v[2:5], v[134:137], v[208:211], v[2:5]
	s_setprio 0
	s_barrier
	s_add_i32 s68, s68, 2
	s_add_u32 s8, s8, 0x100
	s_addc_u32 s9, s9, 0
	s_add_u32 s66, s66, 0x100
	s_addc_u32 s67, s67, 0
	s_cmp_gt_u32 s68, 13
	s_cbranch_scc0 .LBB0_1247
	s_and_b64 vcc, exec, s[24:25]
	s_cbranch_vccz .LBB0_1250
	s_barrier

; __global__ void __launch_bounds__(NTHREADS, 2) fwd_megakernel(Params p_arg) {
	.amdhsa_kernel _Z14fwd_megakernel6Params
		.amdhsa_group_segment_fixed_size 0
		.amdhsa_private_segment_fixed_size 0
		.amdhsa_kernarg_size 416
		.amdhsa_user_sgpr_count 2
		.amdhsa_user_sgpr_dispatch_ptr 0
		.amdhsa_user_sgpr_queue_ptr 0
		.amdhsa_user_sgpr_kernarg_segment_ptr 1
		.amdhsa_user_sgpr_dispatch_id 0
		.amdhsa_user_sgpr_kernarg_preload_length 0
		.amdhsa_user_sgpr_kernarg_preload_offset 0
		.amdhsa_user_sgpr_private_segment_size 0
		.amdhsa_uses_dynamic_stack 0
		.amdhsa_enable_private_segment 0
		.amdhsa_system_sgpr_workgroup_id_x 1
		.amdhsa_system_sgpr_workgroup_id_y 0
		.amdhsa_system_sgpr_workgroup_id_z 0
		.amdhsa_system_sgpr_workgroup_info 0
		.amdhsa_system_vgpr_workitem_id 2
		.amdhsa_next_free_vgpr 256
		.amdhsa_next_free_sgpr 102
		.amdhsa_accum_offset 256
		.amdhsa_reserve_vcc 1
		.amdhsa_float_round_mode_32 0
		.amdhsa_float_round_mode_16_64 0
		.amdhsa_float_denorm_mode_32 3
		.amdhsa_float_denorm_mode_16_64 3
		.amdhsa_dx10_clamp 1
		.amdhsa_ieee_mode 1
		.amdhsa_fp16_overflow 0
		.amdhsa_tg_split 0
		.amdhsa_exception_fp_ieee_invalid_op 0
		.amdhsa_exception_fp_denorm_src 0
		.amdhsa_exception_fp_ieee_div_zero 0
		.amdhsa_exception_fp_ieee_overflow 0
		.amdhsa_exception_fp_ieee_underflow 0
		.amdhsa_exception_fp_ieee_inexact 0
		.amdhsa_exception_int_div_zero 0
	.end_amdhsa_kernel

; __global__ void __launch_bounds__(NTHREADS, 2) fwd_megakernel(Params p_arg) {
.Lfunc_end0:
	.size	_Z14fwd_megakernel6Params, .Lfunc_end0-_Z14fwd_megakernel6Params
	.set _Z14fwd_megakernel6Params.num_vgpr, 256
	.set _Z14fwd_megakernel6Params.num_agpr, 0
	.set _Z14fwd_megakernel6Params.numbered_sgpr, 102
	.set _Z14fwd_megakernel6Params.num_named_barrier, 0
	.set _Z14fwd_megakernel6Params.private_seg_size, 0
	.set _Z14fwd_megakernel6Params.uses_vcc, 1
	.set _Z14fwd_megakernel6Params.uses_flat_scratch, 0
	.set _Z14fwd_megakernel6Params.has_dyn_sized_stack, 0
	.set _Z14fwd_megakernel6Params.has_recursion, 0
	.set _Z14fwd_megakernel6Params.has_indirect_call, 0

; __global__ void __launch_bounds__(NTHREADS, 2) fwd_megakernel(Params p_arg) {
amdhsa.kernels:
  - .agpr_count:     0
    .args:
      - .offset:         0
        .size:           160
        .value_kind:     by_value
      - .offset:         160
        .size:           4
        .value_kind:     hidden_block_count_x
      - .offset:         164
        .size:           4
        .value_kind:     hidden_block_count_y
      - .offset:         168
        .size:           4
        .value_kind:     hidden_block_count_z
      - .offset:         172
        .size:           2
        .value_kind:     hidden_group_size_x
      - .offset:         174
        .size:           2
        .value_kind:     hidden_group_size_y
      - .offset:         176
        .size:           2
        .value_kind:     hidden_group_size_z
      - .offset:         178
        .size:           2
        .value_kind:     hidden_remainder_x
      - .offset:         180
        .size:           2
        .value_kind:     hidden_remainder_y
      - .offset:         182
        .size:           2
        .value_kind:     hidden_remainder_z
      - .offset:         200
        .size:           8
        .value_kind:     hidden_global_offset_x
      - .offset:         208
        .size:           8
        .value_kind:     hidden_global_offset_y
      - .offset:         216
        .size:           8
        .value_kind:     hidden_global_offset_z
      - .offset:         224
        .size:           2
        .value_kind:     hidden_grid_dims
      - .offset:         248
        .size:           8
        .value_kind:     hidden_multigrid_sync_arg
      - .offset:         280
        .size:           4
        .value_kind:     hidden_dynamic_lds_size
    .group_segment_fixed_size: 0
    .kernarg_segment_align: 8
    .kernarg_segment_size: 416
    .language:       OpenCL C
    .language_version:
      - 2
      - 0
    .max_flat_workgroup_size: 512
    .name:           _Z14fwd_megakernel6Params
    .private_segment_fixed_size: 0
    .sgpr_count:     108
    .sgpr_spill_count: 105
    .symbol:         _Z14fwd_megakernel6Params.kd
    .uniform_work_group_size: 1
    .uses_dynamic_stack: false
    .vgpr_count:     256
    .vgpr_spill_count: 0
    .wavefront_size: 64
